# attention phase only: static s_setprio 1 for the second-resident block of each CU (blocks >= 256) during the static MLA/diff items, reset before dynamic items; on top of mid-stage-barrier GEMM loops
# speedup vs baseline: 1.0023x; 1.0023x over previous
.LBB0_730:
	s_or_b64 exec, exec, s[0:1]
	s_mov_b32 s100, 0
	s_cmpk_ge_u32 s101, 0x100
	s_cbranch_scc0 .Lp4_noprio
	s_setprio 1
.Lp4_noprio:
	v_readlane_b32 s2, v255, 38
	s_mov_b32 s4, s54
	s_waitcnt lgkmcnt(0)
	s_barrier
	s_lshl_b32 s0, s2, 1
	v_cvt_f32_i32_e32 v0, s4
	s_add_i32 s0, s0, s4
	s_ashr_i32 s1, s0, 31
	s_lshl_b64 s[0:1], s[0:1], 2
	v_readlane_b32 s5, v255, 0
	s_add_u32 s0, s5, s0
	v_readlane_b32 s5, v255, 1
	v_mul_f32_e32 v0, 0xbe99999a, v0
	s_addc_u32 s1, s5, s1
	v_mul_f32_e32 v1, 0x3fb8aa3b, v0
	s_mov_b32 s5, 0x3fb8aa3b
	v_fma_f32 v2, v0, s5, -v1
	v_rndne_f32_e32 v3, v1
	v_fmac_f32_e32 v2, 0x32a5705f, v0
	v_sub_f32_e32 v1, v1, v3
	v_add_f32_e32 v1, v1, v2
	s_cmp_eq_u32 s2, 0
	v_exp_f32_e32 v1, v1
	v_cvt_i32_f32_e32 v2, v3
	s_movk_i32 s2, 0x280
	s_cselect_b32 s21, 0x80, 0
	s_cselect_b32 s20, s2, 0x200
	s_lshl_b32 s2, s21, 1
	s_or_b32 s22, s2, s20
	s_mov_b32 s2, 0xc2ce8ed0
	s_ashr_i32 s5, s4, 31
	v_ldexp_f32 v1, v1, v2
	v_cmp_ngt_f32_e32 vcc, s2, v0
	s_mov_b32 s2, 0x42b17218
	s_lshl_b32 s14, s4, 7
	s_bitset1_b32 s22, 10
	v_cndmask_b32_e32 v1, 0, v1, vcc
	v_cmp_nlt_f32_e32 vcc, s2, v0
	s_ashr_i32 s15, s14, 31
	s_lshl_b32 s23, s4, 3
	s_lshl_b64 s[4:5], s[4:5], 2
	v_readlane_b32 s2, v255, 4
	v_readlane_b32 s60, v252, 36
	s_add_u32 s40, s2, s4
	v_readlane_b32 s2, v255, 5
	v_readlane_b32 s62, v252, 38
	v_readlane_b32 s63, v252, 39
	s_addc_u32 s41, s2, s5
	s_lshl_b64 s[4:5], s[14:15], 2
	v_readlane_b32 s64, v252, 40
	v_readlane_b32 s65, v252, 41
	s_mov_b64 s[42:43], s[62:63]
	v_readlane_b32 s66, v252, 42
	v_readlane_b32 s67, v252, 43
	v_readlane_b32 s68, v252, 44
	v_readlane_b32 s69, v252, 45
	s_mov_b64 s[44:45], s[64:65]
	s_add_u32 s42, s42, s4
	v_cndmask_b32_e32 v0, v238, v1, vcc
	v_mov_b32_e32 v1, 0xbf4ccccd
	s_mov_b64 s[46:47], s[66:67]
	s_addc_u32 s43, s43, s5
	v_fmamk_f32 v0, v0, 0x3f19999a, v1
	s_add_u32 s44, s46, s4
	v_add_f32_e32 v195, 1.0, v0
	s_addc_u32 s45, s47, s5
	v_readlane_b32 s61, v252, 37
	v_readlane_b32 s70, v252, 46
	v_readlane_b32 s71, v252, 47
	v_readlane_b32 s72, v252, 48
	v_readlane_b32 s73, v252, 49
	v_readlane_b32 s74, v252, 50
	v_readlane_b32 s75, v252, 51
	s_mov_b64 s[48:49], s[68:69]
	s_branch .LBB0_734

.Lp4_dyn:
	s_setprio 0
	s_mov_b64 s[4:5], exec
	v_readlane_b32 s14, v252, 2
	v_readlane_b32 s15, v252, 3
	s_and_b64 s[14:15], s[4:5], s[14:15]
	s_mov_b64 exec, s[14:15]
	s_cbranch_execz .LBB0_738
	s_mov_b64 s[18:19], exec
	v_mbcnt_lo_u32_b32 v0, s18, 0
	v_mbcnt_hi_u32_b32 v0, s19, v0
	v_cmp_eq_u32_e32 vcc, 0, v0
	s_and_saveexec_b64 s[14:15], vcc
	s_cbranch_execz .LBB0_737
	s_bcnt1_i32_b64 s2, s[18:19]
	v_mov_b32_e32 v1, s2
	global_atomic_add v1, v191, v1, s[0:1] sc0
